# indexer: one static s_setprio 1 for waves 4-7 (the second wave on each SIMD) for the whole phase
# baseline (speedup 1.0000x reference)
; #define LAS __attribute__((address_space(3)))
; __device__ __forceinline__ void indexer_unit(const bf16_t* IQ, const bf16_t* IK, const float* IW, unsigned short* SEL, LAS unsigned char* wlds, int t0, int lane) {
;     const int n16 = lane & 15, slab = lane >> 4;
;     bf16x8 a0[NQI], a1[NQI]; h4_t wa[NQI][4]; int cnt[NQI]; float tau[NQI];
; #pragma unroll
;     for (int q = 0; q < NQI; ++q) { const size_t t = (size_t)(t0 + q);
;         a0[q] = *(const bf16x8*)(IQ + t * 1024 + n16 * 64 + slab * 8); a1[q] = *(const bf16x8*)(IQ + t * 1024 + n16 * 64 + 32 + slab * 8);
;         const f32x4 wv = *(const f32x4*)(IW + t * 16 + slab * 4); const h4_t wh = {(_Float16)wv[0], (_Float16)wv[1], (_Float16)wv[2], (_Float16)wv[3]};
;         const h4_t hz = {(_Float16)0, (_Float16)0, (_Float16)0, (_Float16)0};
; #pragma unroll
;         for (int g = 0; g < 4; ++g) wa[q][g] = (n16 == 4 * g) ? wh : hz;
;         cnt[q] = 0; tau[q] = -INFINITY; }
; __global__ void __launch_bounds__(NTHREADS, 2) mega(Args a) {
;     ...
;                 for (int rep = 0; rep < REP_DIL; ++rep) for (int u = blockIdx.x; u < 1536; u += G) dilated_block(QKV, OG, LSE, lds, u, tid);
;                 __syncthreads();
;                 for (int rep = 0; rep < REP_IDX; ++rep) for (int pr = gw; pr < SEQ / NQI / 2; pr += NGW) {
;                     indexer_unit(IQ, IK, IW, SEL, lds + wave * 16384, (SEQ / NQI - 1 - pr) * NQI, lane); indexer_unit(IQ, IK, IW, SEL, lds + wave * 16384, pr * NQI, lane); }
.LBB0_220:
	s_cmpk_gt_i32 s12, 0x7ff
	s_barrier
	s_cbranch_scc1 .LBB0_1003
	v_readlane_b32 s0, v250, 18
	v_readlane_b32 s1, v251, 0
	s_nop 3
	s_lshl_b32 s82, s0, 14
	s_cmp_lt_u32 s0, 4
	s_cbranch_scc1 .Lix_noprio
	s_setprio 1
.Lix_noprio:
	s_lshl_b32 s1, s1, 3
	v_writelane_b32 v249, s1, 0
	s_add_u32 s38, s90, 0x26300000
	s_addc_u32 s39, s91, 0
	s_add_u32 s40, s90, 0x28300000
	s_addc_u32 s41, s91, 0
	s_add_u32 s42, s90, 0x28500000
	s_addc_u32 s43, s91, 0
	s_add_u32 s44, s90, 0x28600000
	s_addc_u32 s45, s91, 0
	v_and_b32_e32 v190, 15, v182
	v_lshrrev_b32_e32 v191, 4, v182
	v_lshlrev_b32_e32 v184, 7, v190
	v_lshlrev_b32_e32 v188, 4, v191
	v_lshl_add_u32 v187, v182, 2, s82
	v_lshlrev_b32_e32 v189, 1, v182
	v_and_b32_e32 v192, 7, v190
	v_xor_b32_e32 v193, v191, v192
	v_lshl_add_u32 v96, v193, 4, v184
	v_xor_b32_e32 v193, 4, v193
	v_lshl_add_u32 v97, v193, 4, v184
	v_add_u32_e32 v98, 155648, v96
	v_add_u32_e32 v99, 155648, v97
	v_add_u32_e32 v96, 147456, v96
	v_add_u32_e32 v97, 147456, v97
	v_lshl_add_u32 v184, v191, 4, v184
	v_lshrrev_b32_e32 v192, 3, v182
	v_and_b32_e32 v193, 7, v182
	v_xor_b32_e32 v193, v193, v192
	v_lshlrev_b32_e32 v192, 7, v192
	v_lshl_add_u32 v185, v193, 4, v192
	s_lshr_b32 s0, s82, 4
	v_add_u32_e32 v185, s0, v185
	v_cmp_eq_u32_e64 s[8:9], 0, v190
	v_cmp_eq_u32_e64 s[10:11], 4, v190
	v_cmp_eq_u32_e64 s[16:17], 8, v190
	v_cmp_eq_u32_e64 s[22:23], 12, v190

; __global__ void __launch_bounds__(NTHREADS, 2) mega(Args a) {
;     ...
;                 for (int rep = 0; rep < REP_IDX; ++rep) for (int pr = gw; pr < SEQ / NQI / 2; pr += NGW) {
;                     indexer_unit(IQ, IK, IW, SEL, lds + wave * 16384, (SEQ / NQI - 1 - pr) * NQI, lane); indexer_unit(IQ, IK, IW, SEL, lds + wave * 16384, pr * NQI, lane); }
;                 __syncthreads();
.Lix_exit:
	s_setprio 0
	s_nop 0
	v_readlane_b32 s30, v254, 60
	v_readlane_b32 s31, v254, 61
	v_readlane_b32 s36, v254, 62
	v_readlane_b32 s37, v254, 63
	v_readlane_b32 s62, v254, 58
	v_readlane_b32 s63, v254, 59
	v_readlane_b32 s68, v250, 0
	v_readlane_b32 s69, v250, 1
	v_readlane_b32 s70, v250, 2
	v_readlane_b32 s71, v250, 3
	v_readlane_b32 s72, v250, 4
	v_readlane_b32 s73, v250, 5
	v_readlane_b32 s74, v250, 6
	v_readlane_b32 s75, v250, 7
	v_readlane_b32 s76, v250, 8
	v_readlane_b32 s77, v250, 9
	v_readlane_b32 s78, v250, 10
	v_readlane_b32 s79, v250, 11
	v_readlane_b32 s80, v250, 12
	v_readlane_b32 s81, v250, 13
	v_readlane_b32 s82, v250, 14
	v_readlane_b32 s83, v250, 15
	s_nop 3
	s_branch .LBB0_1003
